# v097 plus in-proj K loop as 4 segments of 32 MFMAs per 2 K-tiles (8 barriers instead of 16, LDS reads waited before the barrier, vmcnt(8) DMA waits); later code placement kept modulo 64 bytes
# speedup vs baseline: 1.0046x; 1.0046x over previous
.LBB0_185:
	v_lshl_add_u64 v[8:9], s[70:71], 0, v[176:177]
	v_mov_b32_e32 v129, v177
	v_readlane_b32 s68, v254, 40
	s_lshl_b32 s2, s2, 5
	v_lshl_add_u64 v[10:11], s[70:71], 0, v[128:129]
	v_mov_b32_e32 v133, v177
	v_readlane_b32 s69, v254, 41
	s_add_u32 s68, s68, s88
	s_addc_u32 s69, s69, 0
	s_and_b32 s13, s2, 0x60
	s_add_i32 m0, s60, 0x18000
	v_lshl_add_u64 v[8:9], v[8:9], 0, s[20:21]
	v_lshl_add_u64 v[12:13], s[68:69], 0, v[132:133]
	v_mov_b32_e32 v131, v177
	s_lshl_b32 s12, s1, 13
	s_lshl_b32 s14, s13, 7
	s_waitcnt vmcnt(2)
	s_barrier
	global_load_lds_dwordx4 v[8:9], off
	v_lshl_add_u64 v[8:9], v[10:11], 0, s[20:21]
	s_add_i32 m0, s60, 0x1a000
	s_add_i32 s76, s60, 0x8000
	s_add_i32 s77, s60, 0xa000
	v_lshl_add_u64 v[14:15], s[68:69], 0, v[130:131]
	global_load_lds_dwordx4 v[8:9], off
	v_lshl_add_u64 v[8:9], v[12:13], 0, s[20:21]
	s_mov_b32 m0, s76
	s_add_u32 s2, s70, 0x80080
	global_load_lds_dwordx4 v[8:9], off
	v_lshl_add_u64 v[8:9], v[14:15], 0, s[20:21]
	s_mov_b32 m0, s77
	s_addc_u32 s3, s71, 0
	global_load_lds_dwordx4 v[8:9], off
	s_add_i32 m0, s60, 0x1c000
	v_lshl_add_u64 v[8:9], s[2:3], 0, v[176:177]
	global_load_lds_dwordx4 v[8:9], off
	v_lshl_add_u64 v[8:9], s[2:3], 0, v[128:129]
	s_add_i32 m0, s60, 0x1e000
	v_and_b32_e32 v7, 15, v0
	global_load_lds_dwordx4 v[8:9], off
	v_lshrrev_b32_e32 v8, 1, v0
	v_and_b32_e32 v8, 24, v8
	v_lshlrev_b32_e32 v9, 1, v8
	v_lshlrev_b32_e32 v0, 2, v0
	v_lshl_or_b32 v142, s1, 6, v7
	v_lshl_or_b32 v7, v7, 6, v9
	v_and_b32_e32 v0, 32, v0
	v_bitop3_b32 v9, v7, s12, v0 bitop3:0xde
	v_bitop3_b32 v143, v7, s14, v0 bitop3:0xde
	v_lshlrev_b32_e32 v0, 15, v5
	v_and_b32_e32 v0, 0xffff0000, v0
	v_lshl_add_u32 v0, v4, 12, v0
	v_and_b32_e32 v4, 1, v5
	v_lshl_or_b32 v0, v4, 6, v0
	v_lshl_add_u32 v134, v6, 1, v0
	v_lshlrev_b32_e32 v0, 15, v1
	v_and_b32_e32 v0, 0xffff0000, v0
	s_waitcnt vmcnt(6)
	v_lshl_add_u32 v0, v2, 12, v0
	v_and_b32_e32 v1, 1, v1
	v_lshl_or_b32 v0, v1, 6, v0
	v_readlane_b32 s2, v254, 38
	v_or_b32_e32 v144, s13, v8
	v_mov_b32_e32 v135, v177
	v_lshl_add_u32 v136, v3, 1, v0
	v_mov_b32_e32 v137, v177
	s_mov_b32 s78, 0
	v_add_u32_e32 v145, 0, v9
	v_readlane_b32 s79, v254, 35
	s_mov_b32 s80, s2
	s_barrier
	v_readlane_b32 s3, v254, 39

.LBB0_189:
	s_add_u32 s1, s68, 0xfff80080
	s_addc_u32 s2, s69, -1
	v_add_u32_e32 v154, 0x10000, v143
	ds_read_b128 v[138:141], v154
	ds_read_b128 v[146:149], v154 offset:1024
	ds_read_b128 v[150:153], v154 offset:2048
	ds_read_b128 v[154:157], v154 offset:3072
	s_cmp_eq_u32 s87, 28
	s_cselect_b32 s73, s43, s2
	s_cselect_b32 s72, s81, s1
	s_cselect_b32 s71, s41, s86
	s_cselect_b32 s70, s82, s83
	v_add_u32_e32 v174, 0x14000, v143
	ds_read_b128 v[218:221], v174
	ds_read_b128 v[222:225], v174 offset:1024
	ds_read_b128 v[226:229], v174 offset:2048
	ds_read_b128 v[230:233], v174 offset:3072
	v_lshl_add_u64 v[234:235], s[68:69], 0, v[134:135]
	s_add_i32 m0, s60, 0xc000
	ds_read_b128 v[158:161], v145
	ds_read_b128 v[162:165], v145 offset:1024
	ds_read_b128 v[166:169], v145 offset:2048
	ds_read_b128 v[170:173], v145 offset:3072
	ds_read_b128 v[182:185], v145 offset:4096
	ds_read_b128 v[206:209], v145 offset:5120
	ds_read_b128 v[210:213], v145 offset:6144
	ds_read_b128 v[214:217], v145 offset:7168
	global_load_lds_dwordx4 v[234:235], off
	v_lshl_add_u64 v[234:235], s[68:69], 0, v[136:137]
	s_add_i32 m0, s60, 0xe000
	s_nop 0
	global_load_lds_dwordx4 v[234:235], off
	s_waitcnt lgkmcnt(0)
	s_waitcnt vmcnt(8)
	s_barrier
	s_setprio 1
	v_mfma_f32_16x16x32_bf16 v[124:127], v[138:141], v[158:161], v[124:127]
	v_mfma_f32_16x16x32_bf16 v[120:123], v[150:153], v[158:161], v[120:123]
	v_mfma_f32_16x16x32_bf16 v[116:119], v[138:141], v[166:169], v[116:119]
	v_mfma_f32_16x16x32_bf16 v[108:111], v[150:153], v[166:169], v[108:111]
	v_mfma_f32_16x16x32_bf16 v[100:103], v[138:141], v[182:185], v[100:103]
	v_mfma_f32_16x16x32_bf16 v[92:95], v[150:153], v[182:185], v[92:95]
	v_mfma_f32_16x16x32_bf16 v[84:87], v[138:141], v[210:213], v[84:87]
	v_mfma_f32_16x16x32_bf16 v[76:79], v[150:153], v[210:213], v[76:79]
	v_mfma_f32_16x16x32_bf16 v[124:127], v[146:149], v[162:165], v[124:127]
	v_mfma_f32_16x16x32_bf16 v[120:123], v[154:157], v[162:165], v[120:123]
	v_mfma_f32_16x16x32_bf16 v[116:119], v[146:149], v[170:173], v[116:119]
	v_mfma_f32_16x16x32_bf16 v[108:111], v[154:157], v[170:173], v[108:111]
	v_mfma_f32_16x16x32_bf16 v[100:103], v[146:149], v[206:209], v[100:103]
	v_mfma_f32_16x16x32_bf16 v[92:95], v[154:157], v[206:209], v[92:95]
	v_mfma_f32_16x16x32_bf16 v[84:87], v[146:149], v[214:217], v[84:87]
	v_mfma_f32_16x16x32_bf16 v[76:79], v[154:157], v[214:217], v[76:79]
	v_mfma_f32_16x16x32_bf16 v[112:115], v[218:221], v[158:161], v[112:115]
	v_mfma_f32_16x16x32_bf16 v[104:107], v[226:229], v[158:161], v[104:107]
	v_mfma_f32_16x16x32_bf16 v[96:99], v[218:221], v[166:169], v[96:99]
	v_mfma_f32_16x16x32_bf16 v[88:91], v[226:229], v[166:169], v[88:91]
	v_mfma_f32_16x16x32_bf16 v[80:83], v[218:221], v[182:185], v[80:83]
	v_mfma_f32_16x16x32_bf16 v[72:75], v[226:229], v[182:185], v[72:75]
	v_mfma_f32_16x16x32_bf16 v[68:71], v[218:221], v[210:213], v[68:71]
	v_mfma_f32_16x16x32_bf16 v[64:67], v[226:229], v[210:213], v[64:67]
	v_mfma_f32_16x16x32_bf16 v[112:115], v[222:225], v[162:165], v[112:115]
	v_mfma_f32_16x16x32_bf16 v[104:107], v[230:233], v[162:165], v[104:107]
	v_mfma_f32_16x16x32_bf16 v[96:99], v[222:225], v[170:173], v[96:99]
	v_mfma_f32_16x16x32_bf16 v[88:91], v[230:233], v[170:173], v[88:91]
	v_mfma_f32_16x16x32_bf16 v[80:83], v[222:225], v[206:209], v[80:83]
	v_mfma_f32_16x16x32_bf16 v[72:75], v[230:233], v[206:209], v[72:75]
	v_mfma_f32_16x16x32_bf16 v[68:71], v[222:225], v[214:217], v[68:71]
	v_mfma_f32_16x16x32_bf16 v[64:67], v[230:233], v[214:217], v[64:67]
	s_setprio 0
	s_barrier
	ds_read_b128 v[158:161], v145 offset:16384
	ds_read_b128 v[162:165], v145 offset:17408
	ds_read_b128 v[166:169], v145 offset:18432
	ds_read_b128 v[170:173], v145 offset:19456
	ds_read_b128 v[182:185], v145 offset:20480
	ds_read_b128 v[206:209], v145 offset:21504
	ds_read_b128 v[210:213], v145 offset:22528
	ds_read_b128 v[214:217], v145 offset:23552
	v_lshl_add_u64 v[174:175], s[70:71], 0, v[176:177]
	s_add_i32 m0, s53, 0x10000
	v_lshl_add_u64 v[186:187], s[70:71], 0, v[128:129]
	global_load_lds_dwordx4 v[174:175], off
	s_add_i32 m0, s53, 0x12000
	s_nop 0
	global_load_lds_dwordx4 v[186:187], off
	s_mov_b32 m0, s60
	v_lshl_add_u64 v[200:201], s[72:73], 0, v[132:133]
	v_lshl_add_u64 v[202:203], s[72:73], 0, v[130:131]
	global_load_lds_dwordx4 v[200:201], off
	s_mov_b32 m0, s61
	s_nop 0
	global_load_lds_dwordx4 v[202:203], off
	s_add_u32 s2, s70, 0x80000
	s_addc_u32 s3, s71, 0
	v_lshl_add_u64 v[234:235], s[2:3], 0, v[176:177]
	s_add_i32 m0, s53, 0x14000
	v_lshl_add_u64 v[236:237], s[2:3], 0, v[128:129]
	global_load_lds_dwordx4 v[234:235], off
	s_add_i32 m0, s53, 0x16000
	s_nop 0
	global_load_lds_dwordx4 v[236:237], off
	s_waitcnt lgkmcnt(0)
	s_waitcnt vmcnt(8)
	s_barrier
	s_setprio 1
	v_mfma_f32_16x16x32_bf16 v[60:63], v[138:141], v[158:161], v[60:63]
	v_mfma_f32_16x16x32_bf16 v[56:59], v[150:153], v[158:161], v[56:59]
	v_mfma_f32_16x16x32_bf16 v[52:55], v[138:141], v[166:169], v[52:55]
	v_mfma_f32_16x16x32_bf16 v[44:47], v[150:153], v[166:169], v[44:47]
	v_mfma_f32_16x16x32_bf16 v[36:39], v[138:141], v[182:185], v[36:39]
	v_mfma_f32_16x16x32_bf16 v[28:31], v[150:153], v[182:185], v[28:31]
	v_mfma_f32_16x16x32_bf16 v[20:23], v[138:141], v[210:213], v[20:23]
	v_mfma_f32_16x16x32_bf16 v[12:15], v[150:153], v[210:213], v[12:15]
	v_mfma_f32_16x16x32_bf16 v[60:63], v[146:149], v[162:165], v[60:63]
	v_mfma_f32_16x16x32_bf16 v[56:59], v[154:157], v[162:165], v[56:59]
	v_mfma_f32_16x16x32_bf16 v[52:55], v[146:149], v[170:173], v[52:55]
	v_mfma_f32_16x16x32_bf16 v[44:47], v[154:157], v[170:173], v[44:47]
	v_mfma_f32_16x16x32_bf16 v[36:39], v[146:149], v[206:209], v[36:39]
	v_mfma_f32_16x16x32_bf16 v[28:31], v[154:157], v[206:209], v[28:31]
	v_mfma_f32_16x16x32_bf16 v[20:23], v[146:149], v[214:217], v[20:23]
	v_mfma_f32_16x16x32_bf16 v[12:15], v[154:157], v[214:217], v[12:15]
	v_mfma_f32_16x16x32_bf16 v[48:51], v[218:221], v[158:161], v[48:51]
	v_mfma_f32_16x16x32_bf16 v[40:43], v[226:229], v[158:161], v[40:43]
	v_mfma_f32_16x16x32_bf16 v[32:35], v[218:221], v[166:169], v[32:35]
	v_mfma_f32_16x16x32_bf16 v[24:27], v[226:229], v[166:169], v[24:27]
	v_mfma_f32_16x16x32_bf16 v[16:19], v[218:221], v[182:185], v[16:19]
	v_mfma_f32_16x16x32_bf16 v[8:11], v[226:229], v[182:185], v[8:11]
	v_mfma_f32_16x16x32_bf16 v[4:7], v[218:221], v[210:213], v[4:7]
	v_mfma_f32_16x16x32_bf16 v[0:3], v[226:229], v[210:213], v[0:3]
	v_mfma_f32_16x16x32_bf16 v[48:51], v[222:225], v[162:165], v[48:51]
	v_mfma_f32_16x16x32_bf16 v[40:43], v[230:233], v[162:165], v[40:43]
	v_mfma_f32_16x16x32_bf16 v[32:35], v[222:225], v[170:173], v[32:35]
	v_mfma_f32_16x16x32_bf16 v[24:27], v[230:233], v[170:173], v[24:27]
	v_mfma_f32_16x16x32_bf16 v[16:19], v[222:225], v[206:209], v[16:19]
	v_mfma_f32_16x16x32_bf16 v[8:11], v[230:233], v[206:209], v[8:11]
	v_mfma_f32_16x16x32_bf16 v[4:7], v[222:225], v[214:217], v[4:7]
	v_mfma_f32_16x16x32_bf16 v[0:3], v[230:233], v[214:217], v[0:3]
	s_setprio 0
	s_barrier
	v_add_u32_e32 v154, 0x18000, v143
	ds_read_b128 v[138:141], v154
	ds_read_b128 v[146:149], v154 offset:1024
	ds_read_b128 v[150:153], v154 offset:2048
	ds_read_b128 v[154:157], v154 offset:3072
	v_add_u32_e32 v188, 0x1c000, v143
	ds_read_b128 v[218:221], v188
	ds_read_b128 v[222:225], v188 offset:1024
	ds_read_b128 v[226:229], v188 offset:2048
	ds_read_b128 v[230:233], v188 offset:3072
	s_add_u32 s2, s72, 0x80000
	s_addc_u32 s3, s73, 0
	s_mov_b32 m0, s74
	v_lshl_add_u64 v[204:205], s[2:3], 0, v[132:133]
	ds_read_b128 v[158:161], v145 offset:32768
	ds_read_b128 v[162:165], v145 offset:33792
	ds_read_b128 v[166:169], v145 offset:34816
	ds_read_b128 v[170:173], v145 offset:35840
	ds_read_b128 v[182:185], v145 offset:36864
	ds_read_b128 v[206:209], v145 offset:37888
	ds_read_b128 v[210:213], v145 offset:38912
	ds_read_b128 v[214:217], v145 offset:39936
	global_load_lds_dwordx4 v[204:205], off
	v_lshl_add_u64 v[204:205], s[2:3], 0, v[130:131]
	s_mov_b32 m0, s75
	s_nop 0
	global_load_lds_dwordx4 v[204:205], off
	s_waitcnt lgkmcnt(0)
	s_waitcnt vmcnt(8)
	s_barrier
	s_setprio 1
	v_mfma_f32_16x16x32_bf16 v[124:127], v[138:141], v[158:161], v[124:127]
	v_mfma_f32_16x16x32_bf16 v[120:123], v[150:153], v[158:161], v[120:123]
	v_mfma_f32_16x16x32_bf16 v[116:119], v[138:141], v[166:169], v[116:119]
	v_mfma_f32_16x16x32_bf16 v[108:111], v[150:153], v[166:169], v[108:111]
	v_mfma_f32_16x16x32_bf16 v[100:103], v[138:141], v[182:185], v[100:103]
	v_mfma_f32_16x16x32_bf16 v[92:95], v[150:153], v[182:185], v[92:95]
	v_mfma_f32_16x16x32_bf16 v[84:87], v[138:141], v[210:213], v[84:87]
	v_mfma_f32_16x16x32_bf16 v[76:79], v[150:153], v[210:213], v[76:79]
	v_mfma_f32_16x16x32_bf16 v[124:127], v[146:149], v[162:165], v[124:127]
	v_mfma_f32_16x16x32_bf16 v[120:123], v[154:157], v[162:165], v[120:123]
	v_mfma_f32_16x16x32_bf16 v[116:119], v[146:149], v[170:173], v[116:119]
	v_mfma_f32_16x16x32_bf16 v[108:111], v[154:157], v[170:173], v[108:111]
	v_mfma_f32_16x16x32_bf16 v[100:103], v[146:149], v[206:209], v[100:103]
	v_mfma_f32_16x16x32_bf16 v[92:95], v[154:157], v[206:209], v[92:95]
	v_mfma_f32_16x16x32_bf16 v[84:87], v[146:149], v[214:217], v[84:87]
	v_mfma_f32_16x16x32_bf16 v[76:79], v[154:157], v[214:217], v[76:79]
	v_mfma_f32_16x16x32_bf16 v[112:115], v[218:221], v[158:161], v[112:115]
	v_mfma_f32_16x16x32_bf16 v[104:107], v[226:229], v[158:161], v[104:107]
	v_mfma_f32_16x16x32_bf16 v[96:99], v[218:221], v[166:169], v[96:99]
	v_mfma_f32_16x16x32_bf16 v[88:91], v[226:229], v[166:169], v[88:91]
	v_mfma_f32_16x16x32_bf16 v[80:83], v[218:221], v[182:185], v[80:83]
	v_mfma_f32_16x16x32_bf16 v[72:75], v[226:229], v[182:185], v[72:75]
	v_mfma_f32_16x16x32_bf16 v[68:71], v[218:221], v[210:213], v[68:71]
	v_mfma_f32_16x16x32_bf16 v[64:67], v[226:229], v[210:213], v[64:67]
	v_mfma_f32_16x16x32_bf16 v[112:115], v[222:225], v[162:165], v[112:115]
	v_mfma_f32_16x16x32_bf16 v[104:107], v[230:233], v[162:165], v[104:107]
	v_mfma_f32_16x16x32_bf16 v[96:99], v[222:225], v[170:173], v[96:99]
	v_mfma_f32_16x16x32_bf16 v[88:91], v[230:233], v[170:173], v[88:91]
	v_mfma_f32_16x16x32_bf16 v[80:83], v[222:225], v[206:209], v[80:83]
	v_mfma_f32_16x16x32_bf16 v[72:75], v[230:233], v[206:209], v[72:75]
	v_mfma_f32_16x16x32_bf16 v[68:71], v[222:225], v[214:217], v[68:71]
	v_mfma_f32_16x16x32_bf16 v[64:67], v[230:233], v[214:217], v[64:67]
	s_setprio 0
	s_barrier
	ds_read_b128 v[158:161], v145 offset:49152
	ds_read_b128 v[162:165], v145 offset:50176
	ds_read_b128 v[166:169], v145 offset:51200
	ds_read_b128 v[170:173], v145 offset:52224
	ds_read_b128 v[182:185], v145 offset:53248
	ds_read_b128 v[206:209], v145 offset:54272
	ds_read_b128 v[210:213], v145 offset:55296
	ds_read_b128 v[214:217], v145 offset:56320
	v_lshl_add_u64 v[174:175], v[174:175], 0, s[20:21]
	s_add_i32 m0, s53, 0x18000
	s_nop 0
	global_load_lds_dwordx4 v[174:175], off
	v_lshl_add_u64 v[174:175], v[186:187], 0, s[20:21]
	s_add_i32 m0, s53, 0x1a000
	s_nop 0
	global_load_lds_dwordx4 v[174:175], off
	s_mov_b32 m0, s76
	v_lshl_add_u64 v[234:235], v[200:201], 0, s[20:21]
	global_load_lds_dwordx4 v[234:235], off
	v_lshl_add_u64 v[234:235], v[202:203], 0, s[20:21]
	s_mov_b32 m0, s77
	s_nop 0
	global_load_lds_dwordx4 v[234:235], off
	s_add_u32 s2, s70, 0x80080
	s_addc_u32 s3, s71, 0
	v_lshl_add_u64 v[236:237], s[2:3], 0, v[176:177]
	s_add_i32 m0, s53, 0x1c000
	s_nop 0
	global_load_lds_dwordx4 v[236:237], off
	v_lshl_add_u64 v[236:237], s[2:3], 0, v[128:129]
	s_add_i32 m0, s53, 0x1e000
	s_nop 0
	global_load_lds_dwordx4 v[236:237], off
	s_waitcnt lgkmcnt(0)
	s_waitcnt vmcnt(8)
	s_barrier
	s_setprio 1
	v_mfma_f32_16x16x32_bf16 v[60:63], v[138:141], v[158:161], v[60:63]
	v_mfma_f32_16x16x32_bf16 v[56:59], v[150:153], v[158:161], v[56:59]
	v_mfma_f32_16x16x32_bf16 v[52:55], v[138:141], v[166:169], v[52:55]
	v_mfma_f32_16x16x32_bf16 v[44:47], v[150:153], v[166:169], v[44:47]
	v_mfma_f32_16x16x32_bf16 v[36:39], v[138:141], v[182:185], v[36:39]
	v_mfma_f32_16x16x32_bf16 v[28:31], v[150:153], v[182:185], v[28:31]
	v_mfma_f32_16x16x32_bf16 v[20:23], v[138:141], v[210:213], v[20:23]
	v_mfma_f32_16x16x32_bf16 v[12:15], v[150:153], v[210:213], v[12:15]
	v_mfma_f32_16x16x32_bf16 v[60:63], v[146:149], v[162:165], v[60:63]
	v_mfma_f32_16x16x32_bf16 v[56:59], v[154:157], v[162:165], v[56:59]
	v_mfma_f32_16x16x32_bf16 v[52:55], v[146:149], v[170:173], v[52:55]
	v_mfma_f32_16x16x32_bf16 v[44:47], v[154:157], v[170:173], v[44:47]
	v_mfma_f32_16x16x32_bf16 v[36:39], v[146:149], v[206:209], v[36:39]
	v_mfma_f32_16x16x32_bf16 v[28:31], v[154:157], v[206:209], v[28:31]
	v_mfma_f32_16x16x32_bf16 v[20:23], v[146:149], v[214:217], v[20:23]
	v_mfma_f32_16x16x32_bf16 v[12:15], v[154:157], v[214:217], v[12:15]
	v_mfma_f32_16x16x32_bf16 v[48:51], v[218:221], v[158:161], v[48:51]
	v_mfma_f32_16x16x32_bf16 v[40:43], v[226:229], v[158:161], v[40:43]
	v_mfma_f32_16x16x32_bf16 v[32:35], v[218:221], v[166:169], v[32:35]
	v_mfma_f32_16x16x32_bf16 v[24:27], v[226:229], v[166:169], v[24:27]
	v_mfma_f32_16x16x32_bf16 v[16:19], v[218:221], v[182:185], v[16:19]
	v_mfma_f32_16x16x32_bf16 v[8:11], v[226:229], v[182:185], v[8:11]
	v_mfma_f32_16x16x32_bf16 v[4:7], v[218:221], v[210:213], v[4:7]
	v_mfma_f32_16x16x32_bf16 v[0:3], v[226:229], v[210:213], v[0:3]
	v_mfma_f32_16x16x32_bf16 v[48:51], v[222:225], v[162:165], v[48:51]
	v_mfma_f32_16x16x32_bf16 v[40:43], v[230:233], v[162:165], v[40:43]
	v_mfma_f32_16x16x32_bf16 v[32:35], v[222:225], v[170:173], v[32:35]
	v_mfma_f32_16x16x32_bf16 v[24:27], v[230:233], v[170:173], v[24:27]
	v_mfma_f32_16x16x32_bf16 v[16:19], v[222:225], v[206:209], v[16:19]
	v_mfma_f32_16x16x32_bf16 v[8:11], v[230:233], v[206:209], v[8:11]
	v_mfma_f32_16x16x32_bf16 v[4:7], v[222:225], v[214:217], v[4:7]
	v_mfma_f32_16x16x32_bf16 v[0:3], v[230:233], v[214:217], v[0:3]
	s_setprio 0
	s_add_i32 s87, s87, 2
	s_add_u32 s68, s68, 0x100
	s_addc_u32 s69, s69, 0
	s_add_u32 s83, s83, 0x100
	s_addc_u32 s86, s86, 0
	s_cmp_gt_u32 s87, 29
	s_barrier
	s_cbranch_scc0 .LBB0_189
	s_nop 0
	s_nop 0
	s_nop 0
	s_nop 0
	s_nop 0
	s_nop 0
	s_nop 0
	s_nop 0
	s_nop 0
	s_nop 0
	s_nop 0
	s_nop 0
	s_cmp_eq_u32 s88, 0
	s_cbranch_scc1 .Lrs_skip
	s_add_i32 s98, s80, 1
	s_nop 0
	s_cmp_eq_u32 s89, s98
	s_cbranch_scc1 .Lrs_mul
	v_readlane_b32 s98, v255, 1
	v_readlane_b32 s99, v255, 2
	v_lshl_add_u32 v200, s80, 8, v142
	v_bfe_u32 v201, v144, 3, 2
	v_lshlrev_b32_e32 v201, 5, v201
	v_lshl_add_u32 v200, v200, 7, v201
	v_add_u32_e32 v201, 0x1000, v200
	v_add_u32_e32 v202, 0x4000, v200
	v_add_u32_e32 v203, 0x5000, v200
	v_mbcnt_lo_u32_b32 v204, -1, 0
	v_mbcnt_hi_u32_b32 v204, -1, v204
	v_xor_b32_e32 v205, 16, v204
	v_xor_b32_e32 v204, 32, v204
	v_lshlrev_b32_e32 v205, 2, v205
	v_lshlrev_b32_e32 v204, 2, v204
	global_load_dwordx4 v[208:211], v200, s[98:99]
	global_load_dwordx4 v[212:215], v200, s[98:99] offset:16
	global_load_dwordx4 v[216:219], v200, s[98:99] offset:2048
	global_load_dwordx4 v[220:223], v200, s[98:99] offset:2064
	global_load_dwordx4 v[224:227], v201, s[98:99]
	global_load_dwordx4 v[228:231], v201, s[98:99] offset:16
	global_load_dwordx4 v[232:235], v201, s[98:99] offset:2048
	global_load_dwordx4 v[236:239], v201, s[98:99] offset:2064
	s_waitcnt vmcnt(0)
	v_add_f32_e32 v208, v208, v209
	v_add_f32_e32 v210, v210, v211
	v_add_f32_e32 v212, v212, v213
	v_add_f32_e32 v214, v214, v215
	v_add_f32_e32 v208, v208, v210
	v_add_f32_e32 v212, v212, v214
	v_add_f32_e32 v190, v208, v212
	v_add_f32_e32 v216, v216, v217
	v_add_f32_e32 v218, v218, v219
	v_add_f32_e32 v220, v220, v221
	v_add_f32_e32 v222, v222, v223
	v_add_f32_e32 v216, v216, v218
	v_add_f32_e32 v220, v220, v222
	v_add_f32_e32 v191, v216, v220
	v_add_f32_e32 v224, v224, v225
	v_add_f32_e32 v226, v226, v227
	v_add_f32_e32 v228, v228, v229
	v_add_f32_e32 v230, v230, v231
	v_add_f32_e32 v224, v224, v226
	v_add_f32_e32 v228, v228, v230
	v_add_f32_e32 v192, v224, v228
	v_add_f32_e32 v232, v232, v233
	v_add_f32_e32 v234, v234, v235
	v_add_f32_e32 v236, v236, v237
	v_add_f32_e32 v238, v238, v239
	v_add_f32_e32 v232, v232, v234
	v_add_f32_e32 v236, v236, v238
	v_add_f32_e32 v194, v232, v236
	global_load_dwordx4 v[208:211], v202, s[98:99]
	global_load_dwordx4 v[212:215], v202, s[98:99] offset:16
	global_load_dwordx4 v[216:219], v202, s[98:99] offset:2048
	global_load_dwordx4 v[220:223], v202, s[98:99] offset:2064
	global_load_dwordx4 v[224:227], v203, s[98:99]
	global_load_dwordx4 v[228:231], v203, s[98:99] offset:16
	global_load_dwordx4 v[232:235], v203, s[98:99] offset:2048
	global_load_dwordx4 v[236:239], v203, s[98:99] offset:2064
	s_waitcnt vmcnt(0)
	v_add_f32_e32 v208, v208, v209
	v_add_f32_e32 v210, v210, v211
	v_add_f32_e32 v212, v212, v213
	v_add_f32_e32 v214, v214, v215
	v_add_f32_e32 v208, v208, v210
	v_add_f32_e32 v212, v212, v214
	v_add_f32_e32 v195, v208, v212
	v_add_f32_e32 v216, v216, v217
	v_add_f32_e32 v218, v218, v219
	v_add_f32_e32 v220, v220, v221
	v_add_f32_e32 v222, v222, v223
	v_add_f32_e32 v216, v216, v218
	v_add_f32_e32 v220, v220, v222
	v_add_f32_e32 v196, v216, v220
	v_add_f32_e32 v224, v224, v225
	v_add_f32_e32 v226, v226, v227
	v_add_f32_e32 v228, v228, v229
	v_add_f32_e32 v230, v230, v231
	v_add_f32_e32 v224, v224, v226
	v_add_f32_e32 v228, v228, v230
	v_add_f32_e32 v198, v224, v228
	v_add_f32_e32 v232, v232, v233
	v_add_f32_e32 v234, v234, v235
	v_add_f32_e32 v236, v236, v237
	v_add_f32_e32 v238, v238, v239
	v_add_f32_e32 v232, v232, v234
	v_add_f32_e32 v236, v236, v238
	v_add_f32_e32 v248, v232, v236
	ds_bpermute_b32 v240, v205, v190
	ds_bpermute_b32 v241, v205, v191
	ds_bpermute_b32 v242, v205, v192
	ds_bpermute_b32 v243, v205, v194
	ds_bpermute_b32 v244, v205, v195
	ds_bpermute_b32 v245, v205, v196
	ds_bpermute_b32 v246, v205, v198
	ds_bpermute_b32 v247, v205, v248
	s_waitcnt lgkmcnt(0)
	v_add_f32_e32 v190, v190, v240
	v_add_f32_e32 v191, v191, v241
	v_add_f32_e32 v192, v192, v242
	v_add_f32_e32 v194, v194, v243
	v_add_f32_e32 v195, v195, v244
	v_add_f32_e32 v196, v196, v245
	v_add_f32_e32 v198, v198, v246
	v_add_f32_e32 v248, v248, v247
	ds_bpermute_b32 v240, v204, v190
	ds_bpermute_b32 v241, v204, v191
	ds_bpermute_b32 v242, v204, v192
	ds_bpermute_b32 v243, v204, v194
	ds_bpermute_b32 v244, v204, v195
	ds_bpermute_b32 v245, v204, v196
	ds_bpermute_b32 v246, v204, v198
	ds_bpermute_b32 v247, v204, v248
	s_waitcnt lgkmcnt(0)
	v_add_f32_e32 v190, v190, v240
	v_add_f32_e32 v191, v191, v241
	v_add_f32_e32 v192, v192, v242
	v_add_f32_e32 v194, v194, v243
	v_add_f32_e32 v195, v195, v244
	v_add_f32_e32 v196, v196, v245
	v_add_f32_e32 v198, v198, v246
	v_add_f32_e32 v248, v248, v247
	v_mul_f32_e32 v190, 0x3a000000, v190
	v_add_f32_e32 v190, 0x358637bd, v190
	v_mul_f32_e32 v191, 0x3a000000, v191
	v_add_f32_e32 v191, 0x358637bd, v191
	v_mul_f32_e32 v192, 0x3a000000, v192
	v_add_f32_e32 v192, 0x358637bd, v192
	v_mul_f32_e32 v194, 0x3a000000, v194
	v_add_f32_e32 v194, 0x358637bd, v194
	v_mul_f32_e32 v195, 0x3a000000, v195
	v_add_f32_e32 v195, 0x358637bd, v195
	v_mul_f32_e32 v196, 0x3a000000, v196
	v_add_f32_e32 v196, 0x358637bd, v196
	v_mul_f32_e32 v198, 0x3a000000, v198
	v_add_f32_e32 v198, 0x358637bd, v198
	v_mul_f32_e32 v248, 0x3a000000, v248
	v_add_f32_e32 v248, 0x358637bd, v248
	v_rsq_f32_e32 v190, v190
	v_rsq_f32_e32 v191, v191
	v_rsq_f32_e32 v192, v192
	v_rsq_f32_e32 v194, v194
	v_rsq_f32_e32 v195, v195
	v_rsq_f32_e32 v196, v196
	v_rsq_f32_e32 v198, v198
	v_rsq_f32_e32 v248, v248
	s_add_i32 s89, s80, 1
